# P5->P6 split: per-wave C5a arrive in P5 loop, P6 unit remap c^128 so the WGs without a 5th P5 unit run Uq early and take the double Ukv load
# baseline (speedup 1.0000x reference)
.LBB0_701:
	s_add_i32 s70, s70, 1
	s_cmp_lg_u32 s70, 4
	s_cbranch_scc1 .Lc5a_skip
	s_waitcnt vmcnt(0)
	v_readlane_b32 s8, v254, 8
	v_readlane_b32 s9, v254, 9
	s_and_b32 s3, s86, 7
	s_lshl_b32 s3, s3, 8
	s_add_u32 s8, s8, s3
	s_addc_u32 s9, s9, 0
	v_mov_b32_e32 v0, 0
	v_mov_b32_e32 v1, 1
	s_mov_b64 s[14:15], exec
	s_mov_b64 exec, 1
	global_atomic_add v0, v1, s[8:9] offset:2176
	s_mov_b64 exec, s[14:15]
.Lc5a_skip:
	s_mul_i32 s3, s70, s90
	s_mul_hi_u32 s8, s70, s87
	s_add_i32 s8, s8, s3
	s_mul_i32 s3, s70, s87
	s_add_u32 s58, s3, s86
	s_addc_u32 s59, s8, s88
	v_cmp_gt_i64_e32 vcc, s[58:59], v[166:167]
	v_cmp_lt_i64_e64 s[8:9], s[58:59], v[164:165]
	s_cbranch_vccnz .LBB0_703
	s_ashr_i32 s3, s58, 31
	s_lshr_b32 s3, s3, 29
	s_add_i32 s3, s58, s3
	s_ashr_i32 s11, s3, 3
	s_and_b32 s3, s3, -8
	s_sub_i32 s3, s58, s3
	s_cmp_lt_i32 s3, 0
	s_cselect_b32 s14, s29, 0x90
	s_mul_i32 s3, s14, s3
	s_add_i32 s3, s3, s11
	s_mul_hi_i32 s11, s3, 0x38e38e39
	s_lshr_b32 s14, s11, 31
	s_ashr_i32 s11, s11, 4
	s_add_i32 s11, s11, s14
	s_lshl_b32 s14, s11, 3
	s_sub_i32 s15, 0x80, s14
	s_min_i32 s15, s15, 8
	s_abs_i32 s28, s15
	v_cvt_f32_u32_e32 v0, s28
	s_sub_i32 s55, 0, s28
	s_mulk_i32 s11, 0x48
	s_sub_i32 s3, s3, s11
	v_rcp_iflag_f32_e32 v0, v0
	s_abs_i32 s11, s3
	s_xor_b32 s54, s3, s15
	s_ashr_i32 s54, s54, 31
	v_mul_f32_e32 v0, 0x4f7ffffe, v0
	v_cvt_u32_f32_e32 v0, v0
	s_nop 0
	v_readfirstlane_b32 s56, v0
	s_mul_i32 s55, s55, s56
	s_mul_hi_u32 s55, s56, s55
	s_add_i32 s56, s56, s55
	s_mul_hi_u32 s55, s11, s56
	s_mul_i32 s56, s55, s28
	s_sub_i32 s11, s11, s56
	s_add_i32 s57, s55, 1
	s_sub_i32 s56, s11, s28
	s_cmp_ge_u32 s11, s28
	s_cselect_b32 s55, s57, s55
	s_cselect_b32 s11, s56, s11
	s_add_i32 s56, s55, 1
	s_cmp_ge_u32 s11, s28
	s_cselect_b32 s11, s56, s55
	s_xor_b32 s11, s11, s54
	s_sub_i32 s54, s11, s54
	s_mul_i32 s11, s54, s15
	s_sub_i32 s3, s3, s11
	s_add_i32 s56, s3, s14

.LBB0_790:
	v_mbcnt_lo_u32_b32 v0, -1, 0
	v_mbcnt_hi_u32_b32 v0, -1, v0
	s_waitcnt vmcnt(0)
	s_waitcnt lgkmcnt(0)
	v_or_b32_e32 v0, s89, v0
	v_cmp_eq_u32_e32 vcc, 0, v0
	s_barrier
	s_and_saveexec_b64 s[0:1], vcc
	s_xor_b64 s[0:1], exec, s[0:1]
	s_cbranch_execz .LBB0_843
	s_add_i32 s2, 0, 0x22028
	v_mov_b32_e32 v0, s2
	s_waitcnt vmcnt(0) expcnt(0) lgkmcnt(0)
	ds_read_b32 v2, v0
	s_add_i32 s2, 0, 0x2202c
	v_mov_b32_e32 v0, s2
	ds_read_b32 v0, v0
	s_waitcnt lgkmcnt(0)
	v_readfirstlane_b32 s2, v2
	v_readfirstlane_b32 s3, v0
	s_xor_b32 s2, s2, 32
	s_xor_b32 s3, s3, 1
	s_or_b32 s2, s2, s3
	s_cmp_lg_u32 s2, 0
	s_cbranch_scc1 .Lsplit5_full
	v_readlane_b32 s2, v254, 8
	v_readlane_b32 s3, v254, 9
	s_and_b32 s4, s86, 7
	s_lshl_b32 s4, s4, 8
	s_add_u32 s2, s2, s4
	s_addc_u32 s3, s3, 0
	v_mov_b32_e32 v16, 0
	v_mov_b32_e32 v17, 1
	global_atomic_add v16, v17, s[2:3] offset:2240
	s_branch .LBB0_843
.Lsplit5_full:
	s_waitcnt lgkmcnt(1)
	v_cmp_ne_u32_e32 vcc, 0, v2
	s_cbranch_vccnz .LBB0_806
	s_add_u32 s2, s66, 0x1000
	s_addc_u32 s3, s67, 0
	s_add_u32 s4, s66, 0x1100
	s_addc_u32 s5, s67, 0
	s_add_u32 s6, s66, 0x1200
	s_addc_u32 s7, s67, 0
	s_add_u32 s8, s66, 0x1300
	s_addc_u32 s9, s67, 0
	s_mov_b32 s10, 1
	v_mov_b32_e32 v16, 0
	s_branch .LBB0_794
.LBB0_793:
	s_and_b64 vcc, exec, s[38:39]
	s_cbranch_vccnz .LBB0_801

.LBB0_843:
	s_or_b64 exec, exec, s[0:1]
	s_xor_b32 s86, s86, 0x80
	s_xor_b32 s61, s61, 16
	v_mov_b32_e32 v0, 0x22028
	ds_read_b32 v1, v0
	ds_read_b32 v0, v0 offset:4
	s_waitcnt lgkmcnt(0)
	v_readfirstlane_b32 s2, v1
	v_readfirstlane_b32 s3, v0
	s_xor_b32 s2, s2, 32
	s_xor_b32 s3, s3, 1
	s_or_b32 s2, s2, s3
	s_cmp_lg_u32 s2, 0
	s_cbranch_scc1 .Lp5_done
	v_readlane_b32 s2, v254, 8
	v_readlane_b32 s3, v254, 9
	s_and_b32 s4, s86, 7
	s_lshl_b32 s4, s4, 8
	s_add_u32 s2, s2, s4
	s_addc_u32 s3, s3, 0
	s_cmp_lt_u32 s61, 16
	s_cselect_b32 s4, 0, 64
	s_cselect_b32 s5, 0x100, 32
	s_add_u32 s2, s2, s4
	s_addc_u32 s3, s3, 0
	v_mov_b32_e32 v0, 0
.Lp5_poll:
	global_load_dword v1, v0, s[2:3] offset:2176 sc1
	s_waitcnt vmcnt(0)
	v_readfirstlane_b32 s4, v1
	s_cmp_lt_u32 s4, s5
	s_cbranch_scc0 .Lp5_got
	s_sleep 1
	s_branch .Lp5_poll

.Lp5_done:
	s_cmpk_lt_i32 s86, 0x100
	s_waitcnt lgkmcnt(0)
	s_barrier
	s_cselect_b64 s[0:1], -1, 0
	v_mbcnt_lo_u32_b32 v0, -1, 0
	v_mbcnt_hi_u32_b32 v0, -1, v0
	s_and_b64 vcc, exec, s[0:1]
	v_or_b32_e32 v16, s89, v0
	s_nop 0
	v_readfirstlane_b32 s4, v16
	s_cbranch_vccz .LBB0_845
	s_lshl_b32 s6, s62, 5
	s_mul_i32 s5, s62, 33
	s_and_b64 s[2:3], s[22:23], exec
	s_cselect_b32 s2, s5, s6
	s_add_i32 s2, s2, s61
	s_ashr_i32 s3, s2, 31
	s_lshr_b32 s3, s3, 28
	s_add_i32 s3, s2, s3
	s_ashr_i32 s5, s3, 4
	s_and_b32 s3, s3, 0xfff0
	s_sub_i32 s2, s2, s3
	s_bfe_i32 s3, s2, 0x80000
	s_bfe_u32 s3, s3, 0x3000c
	s_add_i32 s3, s2, s3
	s_bfe_i32 s6, s3, 0x80000
	s_and_b32 s3, s3, 0xf8
	s_sub_i32 s2, s2, s3
	s_lshl_b32 s5, s5, 3
	s_sext_i32_i16 s6, s6
	s_sext_i32_i8 s2, s2
	s_add_i32 s55, s5, s2
	s_ashr_i32 s54, s6, 3

.LBB0_885:
	s_cmp_lt_u32 s61, 16
	s_cbranch_scc0 .Lp6_done
	v_mov_b32_e32 v0, 0x22028
	ds_read_b32 v1, v0
	ds_read_b32 v0, v0 offset:4
	s_waitcnt lgkmcnt(0)
	v_readfirstlane_b32 s2, v1
	v_readfirstlane_b32 s3, v0
	s_xor_b32 s2, s2, 32
	s_xor_b32 s3, s3, 1
	s_or_b32 s2, s2, s3
	s_cmp_lg_u32 s2, 0
	s_cbranch_scc1 .Lp6_done
	v_readlane_b32 s2, v254, 8
	v_readlane_b32 s3, v254, 9
	s_and_b32 s4, s86, 7
	s_lshl_b32 s4, s4, 8
	s_add_u32 s2, s2, s4
	s_addc_u32 s3, s3, 0
	v_mov_b32_e32 v0, 0
.Lp6_poll:
	global_load_dword v1, v0, s[2:3] offset:2240 sc1
	s_waitcnt vmcnt(0)
	v_readfirstlane_b32 s4, v1
	s_cmp_lt_u32 s4, 32
	s_cbranch_scc0 .Lp6_got
	s_sleep 1
	s_branch .Lp6_poll
.Lp6_got:
	buffer_inv sc1
	s_waitcnt vmcnt(0)
.Lp6_done:
	v_readlane_b32 s0, v254, 8
	v_readlane_b32 s2, v254, 10
	v_readlane_b32 s1, v254, 9
	s_add_u32 s2, s0, 0x12200000
	v_writelane_b32 v255, s2, 4
	s_addc_u32 s2, s1, 0
	v_writelane_b32 v255, s2, 5
	s_add_u32 s0, s0, 0x13200000
	v_writelane_b32 v255, s0, 6
	s_addc_u32 s0, s1, 0
	v_mbcnt_lo_u32_b32 v0, -1, 0
	v_mbcnt_hi_u32_b32 v0, -1, v0
	v_writelane_b32 v255, s0, 7
	v_or_b32_e32 v8, s89, v0
	s_cmpk_lt_i32 s86, 0x180
	v_readlane_b32 s3, v254, 11
	v_readfirstlane_b32 s5, v8
	s_cbranch_scc0 .LBB0_901
	v_lshlrev_b32_e32 v0, 4, v8
	v_add_u32_e32 v1, 0x2000, v0
	v_ashrrev_i32_e32 v2, 31, v1
	v_lshrrev_b32_e32 v2, 22, v2
	v_add_u32_e32 v2, v1, v2
	v_ashrrev_i32_e32 v2, 10, v2
	s_and_b64 s[0:1], s[22:23], exec
	v_mul_i32_i24_e32 v3, 0x400, v2
	s_cselect_b32 s0, 49, 48
	v_sub_u32_e32 v1, v1, v3
	s_mul_i32 s0, s0, s62
	v_lshrrev_b32_e32 v3, 4, v1
	s_add_i32 s0, s0, s61
	v_bitop3_b32 v1, v3, v1, 32 bitop3:0x6c
	s_mul_hi_i32 s1, s0, 0x2aaaaaab
	v_ashrrev_i32_e32 v3, 31, v1
	s_lshr_b32 s2, s1, 31
	s_ashr_i32 s1, s1, 2
	v_lshrrev_b32_e32 v3, 26, v3
	s_add_i32 s1, s1, s2
	v_add_u32_e32 v3, v1, v3
	v_lshlrev_b32_e32 v5, 3, v2
	s_lshl_b32 s2, s1, 3
	s_mul_i32 s1, s1, 24
	v_ashrrev_i32_e32 v4, 6, v3
	v_and_b32_e32 v5, -16, v5
	v_and_b32_e32 v3, 0xc0, v3
	s_sub_i32 s0, s0, s1
	v_add_u32_e32 v5, v4, v5
	v_sub_u32_e32 v1, v1, v3
	v_mov_b32_e32 v3, 1
	s_bfe_i32 s1, s0, 0x80000
	v_and_b32_e32 v4, 3, v4
	s_mov_b32 s8, 0x7fffe0
	v_lshrrev_b32_e32 v6, 2, v5
	v_lshlrev_b32_e32 v7, 1, v5
	v_lshlrev_b32_e32 v2, 5, v2
	v_ashrrev_i16_sdwa v1, v3, sext(v1) dst_sel:DWORD dst_unused:UNUSED_PAD src0_sel:DWORD src1_sel:BYTE_0
	s_bfe_u32 s1, s1, 0x3000c
	v_and_or_b32 v4, v5, s8, v4
	v_and_b32_e32 v6, 4, v6
	v_and_b32_e32 v7, 24, v7
	v_and_b32_e32 v2, 32, v2
	v_bfe_i32 v1, v1, 0, 16
	s_add_i32 s1, s0, s1
	v_or3_b32 v4, v4, v6, v7
	v_add_lshl_u32 v1, v2, v1, 1
	s_bfe_i32 s3, s1, 0x80000
	s_and_b32 s1, s1, 0xf8
	v_lshl_add_u32 v128, v4, 9, v1
	v_lshl_add_u32 v130, v5, 9, v1
	v_bfe_i32 v1, v8, 27, 1
	s_sub_i32 s0, s0, s1
	v_lshrrev_b32_e32 v1, 22, v1
	s_sext_i32_i16 s3, s3
	s_sext_i32_i8 s0, s0
	v_add_u32_e32 v1, v0, v1
	s_lshr_b32 s4, s3, 3
	s_add_i32 s26, s2, s0
	v_and_b32_e32 v1, 0xfffffc00, v1
	s_ashr_i32 s27, s26, 31
	s_bfe_i64 s[2:3], s[4:5], 0x100000
	v_sub_u32_e32 v0, v0, v1
	s_lshl_b64 s[0:1], s[26:27], 17
	s_lshl_b64 s[2:3], s[2:3], 17
	v_lshrrev_b32_e32 v1, 4, v0
	v_ashrrev_i32_e32 v4, 31, v8
	s_add_u32 s30, s16, s2
	v_bitop3_b32 v0, v1, v0, 32 bitop3:0x6c
	v_lshrrev_b32_e32 v4, 26, v4
	s_addc_u32 s31, s17, s3
	v_ashrrev_i32_e32 v1, 31, v0
	v_add_u32_e32 v4, v8, v4
	s_add_u32 s34, s12, s0
	v_lshrrev_b32_e32 v1, 26, v1
	v_ashrrev_i32_e32 v4, 6, v4
	s_addc_u32 s35, s13, s1
	s_ashr_i32 s6, s5, 6
	v_add_u32_e32 v1, v0, v1
	v_lshlrev_b32_e32 v5, 3, v4
	s_ashr_i32 s7, s5, 8
	s_lshl_b32 s10, s6, 10
	v_ashrrev_i32_e32 v2, 6, v1
	v_and_b32_e32 v5, -16, v5
	v_and_b32_e32 v1, 0xc0, v1
	s_add_u32 s0, s34, 0x10000
	v_add_u32_e32 v5, v2, v5
	v_sub_u32_e32 v0, v0, v1
	s_addc_u32 s1, s35, 0
	v_and_b32_e32 v2, 3, v2
	v_lshrrev_b32_e32 v6, 2, v5
	v_lshlrev_b32_e32 v7, 1, v5
	v_lshlrev_b32_e32 v4, 5, v4
	v_ashrrev_i16_sdwa v0, v3, sext(v0) dst_sel:DWORD dst_unused:UNUSED_PAD src0_sel:DWORD src1_sel:BYTE_0
	s_add_u32 s2, s30, 0x10000
	v_and_or_b32 v2, v5, s8, v2
	v_and_b32_e32 v6, 4, v6
	v_and_b32_e32 v7, 24, v7
	v_and_b32_e32 v4, 32, v4
	v_bfe_i32 v0, v0, 0, 16
	s_addc_u32 s3, s31, 0
	v_or3_b32 v2, v2, v6, v7
	v_add_lshl_u32 v0, v4, v0, 1
	s_add_i32 s11, s10, 0
	v_lshl_add_u32 v132, v2, 9, v0
	s_add_i32 m0, s11, 0x10000
	v_lshl_add_u32 v134, v5, 9, v0
	global_load_lds_dwordx4 v132, s[30:31]
	s_add_i32 m0, s11, 0x12000
	s_add_i32 s14, s11, 0x2000
	global_load_lds_dwordx4 v128, s[30:31]
	s_add_i32 m0, s11, 0x14000
	s_add_i32 s15, s11, 0x4000
	global_load_lds_dwordx4 v132, s[2:3]
	s_add_i32 m0, s11, 0x16000
	s_add_i32 s27, s11, 0x6000
	global_load_lds_dwordx4 v128, s[2:3]
	s_mov_b32 m0, s11
	v_mov_b32_e32 v133, 0
	global_load_lds_dwordx4 v134, s[34:35]
	s_mov_b32 m0, s14
	v_mov_b32_e32 v129, v133
	global_load_lds_dwordx4 v130, s[34:35]
	s_mov_b32 m0, s15
	v_mov_b32_e32 v135, v133
	global_load_lds_dwordx4 v134, s[0:1]
	s_mov_b32 m0, s27
	v_mov_b32_e32 v131, v133
	global_load_lds_dwordx4 v130, s[0:1]
	s_cmp_eq_u32 s7, 1
	s_mov_b32 s28, 0
	v_lshl_add_u64 v[6:7], s[30:31], 0, v[132:133]
	v_lshl_add_u64 v[4:5], s[30:31], 0, v[128:129]
	v_lshl_add_u64 v[0:1], s[34:35], 0, v[134:135]
	s_cselect_b64 s[0:1], -1, 0
	s_cmp_lg_u32 s7, 1
	v_lshl_add_u64 v[2:3], s[34:35], 0, v[130:131]
	s_cbranch_scc1 .LBB0_888
	s_barrier

.LBB0_901:
	s_xor_b32 s86, s86, 0x80
	v_mbcnt_lo_u32_b32 v0, -1, 0
	v_mbcnt_hi_u32_b32 v0, -1, v0
	s_waitcnt vmcnt(0)
	s_nop 0
	v_or_b32_e32 v0, s89, v0
	v_cmp_eq_u32_e32 vcc, 0, v0
	s_barrier
	s_and_saveexec_b64 s[0:1], vcc
	s_xor_b64 s[0:1], exec, s[0:1]
	s_cbranch_execz .LBB0_954
	s_add_i32 s2, 0, 0x22028
	v_mov_b32_e32 v0, s2
	s_waitcnt vmcnt(0) expcnt(0) lgkmcnt(0)
	ds_read_b32 v2, v0
	s_add_i32 s2, 0, 0x2202c
	v_mov_b32_e32 v0, s2
	ds_read_b32 v0, v0
	s_waitcnt lgkmcnt(0)
	v_readfirstlane_b32 s2, v2
	v_readfirstlane_b32 s3, v0
	s_mov_b32 s32, 1
	s_xor_b32 s2, s2, 32
	s_xor_b32 s3, s3, 1
	s_or_b32 s2, s2, s3
	s_cmp_lg_u32 s2, 0
	s_cbranch_scc1 .Lsplit_full
	v_readlane_b32 s2, v254, 8
	v_readlane_b32 s3, v254, 9
	s_lshl_b32 s4, s78, 8
	s_mov_b32 s32, 0
	s_add_u32 s2, s2, s4
	s_addc_u32 s3, s3, 0
	v_mov_b32_e32 v16, 0
	v_mov_b32_e32 v17, 1
	s_nop 1
	global_atomic_add v16, v17, s[2:3] offset:2048
	s_branch .LBB0_954
